# local attention S-part: the four rpb-bias LDS reads of each key chunk issued together (one LDS latency per chunk instead of four)
# speedup vs baseline: 1.0376x; 1.0013x over previous
; #define LAS __attribute__((address_space(3)))
; __device__ __forceinline__ int kswz(int key) { return ((key >> 1) & 1) | (((key >> 3) & 3) << 1); }
; #define AH_LDK(c, bufi) do { kf[bufi][0] = *(const LAS bf16x8*)(lds + kaddr0 + (c) * kcs); kf[bufi][1] = *(const LAS bf16x8*)(lds + kaddr1 + (c) * kcs); \
;         kf[bufi][2] = *(const LAS bf16x8*)(lds + kaddr0 + (c) * kcs + 512); kf[bufi][3] = *(const LAS bf16x8*)(lds + kaddr1 + (c) * kcs + 512); } while (0)
; template <bool LOC> ...
;     ...
;     AH_LDK(0, 0);
; #pragma unroll
;     for (int c = 0; c < 8; ++c) {
;         if (c < 7) AH_LDK(c + 1, (c + 1) & 1);
;         __builtin_amdgcn_sched_barrier(0);
;         f32x4 t0 = (f32x4){0.f, 0.f, 0.f, 0.f}, t1 = (f32x4){0.f, 0.f, 0.f, 0.f};
;         t0 = __builtin_amdgcn_mfma_f32_16x16x32_bf16(kf[c & 1][0], q0, t0, 0, 0, 0); t1 = __builtin_amdgcn_mfma_f32_16x16x32_bf16(kf[c & 1][2], q0, t1, 0, 0, 0);
;         t0 = __builtin_amdgcn_mfma_f32_16x16x32_bf16(kf[c & 1][1], q1, t0, 0, 0, 0); t1 = __builtin_amdgcn_mfma_f32_16x16x32_bf16(kf[c & 1][3], q1, t1, 0, 0, 0);
; #pragma unroll
;         for (int e = 0; e < 8; ++e) { const float a = (e < 4) ? t0[e] : t1[e - 4];
;             if (LOC) { const float bv = bp[c * RPB_PITCH + e]; const bool ok = (e >= elo) && (e < elo + 16); s[c][e] = ok ? (a * SC + bv) : -INFINITY; }
;             else s[c][e] = a * SC; }
;         __builtin_amdgcn_sched_barrier(0);
;     }
; __device__ __forceinline__ void phase_mixer(const Params& p, LAS unsigned char* lds, int l, bool with_ctx, int G, int tid, int wave, int lane, int rep_attn, int rep_pool) {
;     ...
;             const int kl = (rs - rs0) * 64 + kc0 + kap, ka0 = AT_KL + kl * 128 + ((g ^ kswz(kl)) << 4), ka1 = AT_KL + kl * 128 + (((g + 4) ^ kswz(kl)) << 4);
;             const int vrow = AT_VL + qi * AT_VLP, vch0 = (rs - rs0) * 8 + (kc0 >> 3);
;             const LAS float* bp = (const LAS float*)(lds + AT_RPB) + (rs - r + 7) * RPB_PITCH + RPB_OFF + (kc0 + 8 * g - qc + 15);
;             attn_half<true>(lds, ka0, ka1, 64 * 128, vrow, vch0, 8, 16 * AT_VLP, bp, qs - kc0 - 8 * g, qA0, qA1, mxA, lA, oA, g, qi);
.LBB0_296:
	s_or_b64 exec, exec, s[68:69]
	s_add_i32 s64, s64, -4
	s_min_u32 s64, s64, 56
	v_sub_u32_e32 v36, s64, v26
	v_lshl_add_u32 v24, v36, 13, v128
	v_add_u32_e32 v25, v24, v126
	s_waitcnt lgkmcnt(0)
	s_barrier
	v_add_u32_e32 v26, v24, v127
	ds_read_b128 v[30:33], v25
	ds_read_b128 v[38:41], v25 offset:512
	ds_read_b128 v[42:45], v26
	ds_read_b128 v[46:49], v26 offset:512
	ds_read_b128 v[50:53], v25 offset:8192
	ds_read_b128 v[54:57], v25 offset:8704
	ds_read_b128 v[58:61], v26 offset:8192
	ds_read_b128 v[62:65], v26 offset:8704
	s_sub_i32 s63, s64, s63
	v_lshl_add_u32 v24, s63, 8, v129
	v_add_u32_e32 v27, 0x77c, v24
	s_waitcnt lgkmcnt(7)
	v_mfma_f32_16x16x32_bf16 v[30:33], v[30:33], v[4:7], 0
	ds_read2_b32 v[34:35], v27 offset1:1
	s_waitcnt lgkmcnt(6)
	v_mfma_f32_16x16x32_bf16 v[30:33], v[42:45], v[0:3], v[30:33]
	v_mfma_f32_16x16x32_bf16 v[38:41], v[38:41], v[4:7], 0
	s_waitcnt lgkmcnt(5)
	v_mfma_f32_16x16x32_bf16 v[38:41], v[46:49], v[0:3], v[38:41]
	v_add_u32_e32 v235, 0x784, v24
	v_add_u32_e32 v236, 0x78c, v24
	v_add_u32_e32 v237, 0x794, v24
	ds_read2_b32 v[238:239], v235 offset1:1
	ds_read2_b32 v[240:241], v236 offset1:1
	ds_read2_b32 v[242:243], v237 offset1:1
	s_waitcnt lgkmcnt(0)
	s_nop 3
	v_fmamk_f32 v27, v30, 0x3e38aa3b, v34
	v_cndmask_b32_e64 v30, v222, v27, s[6:7]
	v_fmac_f32_e32 v35, 0x3e38aa3b, v31
	s_nop 0
	v_cndmask_b32_e64 v29, v222, v35, s[8:9]
	s_nop 0
	s_waitcnt lgkmcnt(0)
	v_fmamk_f32 v27, v32, 0x3e38aa3b, v238
	v_cndmask_b32_e64 v32, v222, v27, s[10:11]
	v_fmac_f32_e32 v239, 0x3e38aa3b, v33
	s_nop 0
	v_cndmask_b32_e64 v31, v222, v239, s[12:13]
	s_nop 0
	s_waitcnt lgkmcnt(0)
	v_fmamk_f32 v27, v38, 0x3e38aa3b, v240
	v_cndmask_b32_e64 v34, v222, v27, s[14:15]
	s_nop 0
	v_fmac_f32_e32 v241, 0x3e38aa3b, v39
	s_nop 0
	v_cndmask_b32_e64 v33, v222, v241, s[16:17]
	s_waitcnt lgkmcnt(0)
	v_fmamk_f32 v27, v40, 0x3e38aa3b, v242
	v_fmac_f32_e32 v243, 0x3e38aa3b, v41
	v_cndmask_b32_e64 v43, v222, v27, s[18:19]
	v_cndmask_b32_e64 v41, v222, v243, s[20:21]
	ds_read_b128 v[44:47], v25 offset:16384
	ds_read_b128 v[66:69], v25 offset:16896
	ds_read_b128 v[100:103], v26 offset:16384
	ds_read_b128 v[152:155], v26 offset:16896
	v_mfma_f32_16x16x32_bf16 v[48:51], v[50:53], v[4:7], 0
	v_add_u32_e32 v27, 0x87c, v24
	ds_read2_b32 v[38:39], v27 offset1:1
	v_mfma_f32_16x16x32_bf16 v[48:51], v[58:61], v[0:3], v[48:51]
	v_mfma_f32_16x16x32_bf16 v[52:55], v[54:57], v[4:7], 0
	v_mfma_f32_16x16x32_bf16 v[52:55], v[62:65], v[0:3], v[52:55]
	v_add_u32_e32 v235, 0x884, v24
	v_add_u32_e32 v236, 0x88c, v24
	v_add_u32_e32 v237, 0x894, v24
	ds_read2_b32 v[238:239], v235 offset1:1
	ds_read2_b32 v[240:241], v236 offset1:1
	ds_read2_b32 v[242:243], v237 offset1:1
	s_waitcnt lgkmcnt(0)
	s_nop 4
	v_fmamk_f32 v27, v48, 0x3e38aa3b, v38
	v_cndmask_b32_e64 v37, v222, v27, s[6:7]
	s_nop 0
	v_fmac_f32_e32 v39, 0x3e38aa3b, v49
	s_nop 0
	v_cndmask_b32_e64 v35, v222, v39, s[8:9]
	s_waitcnt lgkmcnt(0)
	v_fmamk_f32 v27, v50, 0x3e38aa3b, v238
	v_cndmask_b32_e64 v39, v222, v27, s[10:11]
	v_fmac_f32_e32 v239, 0x3e38aa3b, v51
	s_nop 0
	v_cndmask_b32_e64 v38, v222, v239, s[12:13]
	s_nop 0
	s_waitcnt lgkmcnt(0)
	v_fmamk_f32 v27, v52, 0x3e38aa3b, v240
	v_cndmask_b32_e64 v42, v222, v27, s[14:15]
	v_fmac_f32_e32 v241, 0x3e38aa3b, v53
	s_nop 0
	v_cndmask_b32_e64 v40, v222, v241, s[16:17]
	s_nop 0
	s_waitcnt lgkmcnt(0)
	v_fmamk_f32 v27, v54, 0x3e38aa3b, v242
	v_fmac_f32_e32 v243, 0x3e38aa3b, v55
	v_cndmask_b32_e64 v51, v222, v27, s[18:19]
	v_cndmask_b32_e64 v49, v222, v243, s[20:21]
	ds_read_b128 v[52:55], v25 offset:24576
	ds_read_b128 v[60:63], v25 offset:25088
	ds_read_b128 v[170:173], v26 offset:24576
	ds_read_b128 v[174:177], v26 offset:25088
	v_mfma_f32_16x16x32_bf16 v[44:47], v[44:47], v[4:7], 0
	v_add_u32_e32 v27, 0x97c, v24
	v_mfma_f32_16x16x32_bf16 v[56:59], v[66:69], v[4:7], 0
	v_mfma_f32_16x16x32_bf16 v[64:67], v[100:103], v[0:3], v[44:47]
	s_nop 4
	ds_read2_b32 v[46:47], v27 offset1:1
	v_mfma_f32_16x16x32_bf16 v[68:71], v[152:155], v[0:3], v[56:59]
	v_add_u32_e32 v235, 0x984, v24
	v_add_u32_e32 v236, 0x98c, v24
	v_add_u32_e32 v237, 0x994, v24
	ds_read2_b32 v[238:239], v235 offset1:1
	ds_read2_b32 v[240:241], v236 offset1:1
	ds_read2_b32 v[242:243], v237 offset1:1
	s_waitcnt lgkmcnt(0)
	v_fmamk_f32 v27, v64, 0x3e38aa3b, v46
	v_cndmask_b32_e64 v45, v222, v27, s[6:7]
	s_nop 0
	s_nop 0
	v_fmac_f32_e32 v47, 0x3e38aa3b, v65
	v_cndmask_b32_e64 v44, v222, v47, s[8:9]
	s_waitcnt lgkmcnt(0)
	v_fmamk_f32 v27, v66, 0x3e38aa3b, v238
	v_cndmask_b32_e64 v47, v222, v27, s[10:11]
	v_fmac_f32_e32 v239, 0x3e38aa3b, v67
	s_nop 0
	v_cndmask_b32_e64 v46, v222, v239, s[12:13]
	s_nop 0
	s_waitcnt lgkmcnt(0)
	v_fmamk_f32 v27, v68, 0x3e38aa3b, v240
	v_cndmask_b32_e64 v50, v222, v27, s[14:15]
	v_fmac_f32_e32 v241, 0x3e38aa3b, v69
	s_nop 0
	v_cndmask_b32_e64 v48, v222, v241, s[16:17]
	s_nop 0
	s_waitcnt lgkmcnt(0)
	v_fmamk_f32 v27, v70, 0x3e38aa3b, v242
	v_fmac_f32_e32 v243, 0x3e38aa3b, v71
	v_cndmask_b32_e64 v59, v222, v27, s[18:19]
	v_cndmask_b32_e64 v57, v222, v243, s[20:21]
	ds_read_b128 v[68:71], v25 offset:32768
	ds_read_b128 v[100:103], v25 offset:33280
	ds_read_b128 v[152:155], v26 offset:32768
	ds_read_b128 v[178:181], v26 offset:33280
	v_mfma_f32_16x16x32_bf16 v[52:55], v[52:55], v[4:7], 0
	v_add_u32_e32 v27, 0xa7c, v24
	v_mfma_f32_16x16x32_bf16 v[64:67], v[170:173], v[0:3], v[52:55]
	v_mfma_f32_16x16x32_bf16 v[60:63], v[60:63], v[4:7], 0
	s_nop 4
	ds_read2_b32 v[54:55], v27 offset1:1
	v_add_u32_e32 v235, 0xa84, v24
	v_add_u32_e32 v236, 0xa8c, v24
	v_add_u32_e32 v237, 0xa94, v24
	ds_read2_b32 v[238:239], v235 offset1:1
	ds_read2_b32 v[240:241], v236 offset1:1
	ds_read2_b32 v[242:243], v237 offset1:1
	s_waitcnt lgkmcnt(0)
; #define AH_LDK(c, bufi) do { kf[bufi][0] = *(const LAS bf16x8*)(lds + kaddr0 + (c) * kcs); kf[bufi][1] = *(const LAS bf16x8*)(lds + kaddr1 + (c) * kcs); \
;         kf[bufi][2] = *(const LAS bf16x8*)(lds + kaddr0 + (c) * kcs + 512); kf[bufi][3] = *(const LAS bf16x8*)(lds + kaddr1 + (c) * kcs + 512); } while (0)
; template <bool LOC> ...
;     ...
;     AH_LDK(0, 0);
; #pragma unroll
;     for (int c = 0; c < 8; ++c) {
;         if (c < 7) AH_LDK(c + 1, (c + 1) & 1);
;         __builtin_amdgcn_sched_barrier(0);
;         f32x4 t0 = (f32x4){0.f, 0.f, 0.f, 0.f}, t1 = (f32x4){0.f, 0.f, 0.f, 0.f};
;         t0 = __builtin_amdgcn_mfma_f32_16x16x32_bf16(kf[c & 1][0], q0, t0, 0, 0, 0); t1 = __builtin_amdgcn_mfma_f32_16x16x32_bf16(kf[c & 1][2], q0, t1, 0, 0, 0);
;         t0 = __builtin_amdgcn_mfma_f32_16x16x32_bf16(kf[c & 1][1], q1, t0, 0, 0, 0); t1 = __builtin_amdgcn_mfma_f32_16x16x32_bf16(kf[c & 1][3], q1, t1, 0, 0, 0);
; #pragma unroll
;         for (int e = 0; e < 8; ++e) { const float a = (e < 4) ? t0[e] : t1[e - 4];
;             if (LOC) { const float bv = bp[c * RPB_PITCH + e]; const bool ok = (e >= elo) && (e < elo + 16); s[c][e] = ok ? (a * SC + bv) : -INFINITY; }
;             else s[c][e] = a * SC; }
;         __builtin_amdgcn_sched_barrier(0);
;     }
	v_fmamk_f32 v27, v64, 0x3e38aa3b, v54
	v_cndmask_b32_e64 v53, v222, v27, s[6:7]
	s_nop 0
	v_fmac_f32_e32 v55, 0x3e38aa3b, v65
	s_nop 0
	v_cndmask_b32_e64 v52, v222, v55, s[8:9]
	v_mfma_f32_16x16x32_bf16 v[60:63], v[174:177], v[0:3], v[60:63]
	s_waitcnt lgkmcnt(0)
	v_fmamk_f32 v27, v66, 0x3e38aa3b, v238
	v_cndmask_b32_e64 v55, v222, v27, s[10:11]
	v_fmac_f32_e32 v239, 0x3e38aa3b, v67
	s_nop 0
	v_cndmask_b32_e64 v54, v222, v239, s[12:13]
	s_nop 0
	s_waitcnt lgkmcnt(0)
	v_fmamk_f32 v27, v60, 0x3e38aa3b, v240
	v_cndmask_b32_e64 v58, v222, v27, s[14:15]
	s_nop 0
	v_fmac_f32_e32 v241, 0x3e38aa3b, v61
	s_nop 0
	v_cndmask_b32_e64 v56, v222, v241, s[16:17]
	s_waitcnt lgkmcnt(0)
	v_fmamk_f32 v27, v62, 0x3e38aa3b, v242
	v_fmac_f32_e32 v243, 0x3e38aa3b, v63
	v_cndmask_b32_e64 v67, v222, v27, s[18:19]
	v_cndmask_b32_e64 v65, v222, v243, s[20:21]
	ds_read_b128 v[170:173], v25 offset:40960
	ds_read_b128 v[174:177], v25 offset:41472
	ds_read_b128 v[182:185], v26 offset:40960
	ds_read_b128 v[186:189], v26 offset:41472
	v_mfma_f32_16x16x32_bf16 v[60:63], v[68:71], v[4:7], 0
	v_add_u32_e32 v27, 0xb7c, v24
	v_mfma_f32_16x16x32_bf16 v[68:71], v[100:103], v[4:7], 0
	v_mfma_f32_16x16x32_bf16 v[100:103], v[152:155], v[0:3], v[60:63]
	s_nop 4
	ds_read2_b32 v[62:63], v27 offset1:1
	v_mfma_f32_16x16x32_bf16 v[68:71], v[178:181], v[0:3], v[68:71]
	v_add_u32_e32 v235, 0xb84, v24
	v_add_u32_e32 v236, 0xb8c, v24
	v_add_u32_e32 v237, 0xb94, v24
	ds_read2_b32 v[238:239], v235 offset1:1
	ds_read2_b32 v[240:241], v236 offset1:1
	ds_read2_b32 v[242:243], v237 offset1:1
	s_waitcnt lgkmcnt(0)
	v_fmamk_f32 v27, v100, 0x3e38aa3b, v62
	v_cndmask_b32_e64 v61, v222, v27, s[6:7]
	s_nop 0
	v_fmac_f32_e32 v63, 0x3e38aa3b, v101
	s_nop 0
	v_cndmask_b32_e64 v60, v222, v63, s[8:9]
	s_waitcnt lgkmcnt(0)
	v_fmamk_f32 v27, v102, 0x3e38aa3b, v238
	v_cndmask_b32_e64 v63, v222, v27, s[10:11]
	v_fmac_f32_e32 v239, 0x3e38aa3b, v103
	s_nop 0
	v_cndmask_b32_e64 v62, v222, v239, s[12:13]
	s_nop 0
	s_waitcnt lgkmcnt(0)
	v_fmamk_f32 v27, v68, 0x3e38aa3b, v240
	v_cndmask_b32_e64 v66, v222, v27, s[14:15]
	s_nop 0
	v_fmac_f32_e32 v241, 0x3e38aa3b, v69
	s_nop 0
	v_cndmask_b32_e64 v64, v222, v241, s[16:17]
	s_waitcnt lgkmcnt(0)
	v_fmamk_f32 v27, v70, 0x3e38aa3b, v242
	v_fmac_f32_e32 v243, 0x3e38aa3b, v71
	v_cndmask_b32_e64 v102, v222, v27, s[18:19]
	v_cndmask_b32_e64 v100, v222, v243, s[20:21]
	ds_read_b128 v[178:181], v25 offset:49152
	ds_read_b128 v[190:193], v25 offset:49664
	ds_read_b128 v[194:197], v26 offset:49152
	ds_read_b128 v[198:201], v26 offset:49664
	v_mfma_f32_16x16x32_bf16 v[68:71], v[170:173], v[4:7], 0
	v_add_u32_e32 v27, 0xc7c, v24
	v_mfma_f32_16x16x32_bf16 v[170:173], v[182:185], v[0:3], v[68:71]
	v_mfma_f32_16x16x32_bf16 v[152:155], v[174:177], v[4:7], 0
	s_nop 4
	ds_read2_b32 v[70:71], v27 offset1:1
	v_add_u32_e32 v235, 0xc84, v24
	v_add_u32_e32 v236, 0xc8c, v24
	v_add_u32_e32 v237, 0xc94, v24
	ds_read2_b32 v[238:239], v235 offset1:1
	ds_read2_b32 v[240:241], v236 offset1:1
	ds_read2_b32 v[242:243], v237 offset1:1
	s_waitcnt lgkmcnt(0)
	v_fmamk_f32 v27, v170, 0x3e38aa3b, v70
	v_cndmask_b32_e64 v69, v222, v27, s[6:7]
	s_nop 0
	s_nop 0
	v_fmac_f32_e32 v71, 0x3e38aa3b, v171
	v_cndmask_b32_e64 v68, v222, v71, s[8:9]
	v_mfma_f32_16x16x32_bf16 v[174:177], v[186:189], v[0:3], v[152:155]
	s_waitcnt lgkmcnt(0)
	v_fmamk_f32 v27, v172, 0x3e38aa3b, v238
	v_cndmask_b32_e64 v71, v222, v27, s[10:11]
	v_fmac_f32_e32 v239, 0x3e38aa3b, v173
	s_nop 0
	v_cndmask_b32_e64 v70, v222, v239, s[12:13]
	s_nop 0
	s_waitcnt lgkmcnt(0)
	v_fmamk_f32 v27, v174, 0x3e38aa3b, v240
	v_cndmask_b32_e64 v101, v222, v27, s[14:15]
	v_fmac_f32_e32 v241, 0x3e38aa3b, v175
	s_nop 0
	v_cndmask_b32_e64 v99, v222, v241, s[16:17]
	s_nop 0
	s_waitcnt lgkmcnt(0)
	v_fmamk_f32 v27, v176, 0x3e38aa3b, v242
	v_fmac_f32_e32 v243, 0x3e38aa3b, v177
	v_cndmask_b32_e64 v155, v222, v27, s[18:19]
	v_cndmask_b32_e64 v153, v222, v243, s[20:21]
	ds_read_b128 v[182:185], v25 offset:57344
	ds_read_b128 v[186:189], v25 offset:57856
	ds_read_b128 v[202:205], v26 offset:57344
	ds_read_b128 v[206:209], v26 offset:57856
	v_mfma_f32_16x16x32_bf16 v[170:173], v[178:181], v[4:7], 0
	v_add_u32_e32 v25, 0xd7c, v24
	ds_read2_b32 v[26:27], v25 offset1:1
	v_mfma_f32_16x16x32_bf16 v[170:173], v[194:197], v[0:3], v[170:173]
	v_mfma_f32_16x16x32_bf16 v[174:177], v[190:193], v[4:7], 0
	v_mfma_f32_16x16x32_bf16 v[174:177], v[198:201], v[0:3], v[174:177]
	v_add_u32_e32 v235, 0xd84, v24
	v_add_u32_e32 v236, 0xd8c, v24
	v_add_u32_e32 v237, 0xd94, v24
	ds_read2_b32 v[238:239], v235 offset1:1
	ds_read2_b32 v[240:241], v236 offset1:1
	ds_read2_b32 v[242:243], v237 offset1:1
	s_waitcnt lgkmcnt(0)
	s_nop 4
	v_fmamk_f32 v25, v170, 0x3e38aa3b, v26
	v_cndmask_b32_e64 v104, v222, v25, s[6:7]
	v_fmac_f32_e32 v27, 0x3e38aa3b, v171
	s_nop 0
	v_cndmask_b32_e64 v103, v222, v27, s[8:9]
	s_nop 0
	s_waitcnt lgkmcnt(0)
	v_fmamk_f32 v25, v172, 0x3e38aa3b, v238
	v_cndmask_b32_e64 v151, v222, v25, s[10:11]
	v_fmac_f32_e32 v239, 0x3e38aa3b, v173
	s_nop 0
	v_cndmask_b32_e64 v105, v222, v239, s[12:13]
	s_nop 0
	s_waitcnt lgkmcnt(0)
	v_fmamk_f32 v25, v174, 0x3e38aa3b, v240
	v_cndmask_b32_e64 v154, v222, v25, s[14:15]
	v_fmac_f32_e32 v241, 0x3e38aa3b, v175
	s_nop 0
	v_cndmask_b32_e64 v152, v222, v241, s[16:17]
	s_nop 0
	s_waitcnt lgkmcnt(0)
; #define AH_LDK(c, bufi) do { kf[bufi][0] = *(const LAS bf16x8*)(lds + kaddr0 + (c) * kcs); kf[bufi][1] = *(const LAS bf16x8*)(lds + kaddr1 + (c) * kcs); \
;         kf[bufi][2] = *(const LAS bf16x8*)(lds + kaddr0 + (c) * kcs + 512); kf[bufi][3] = *(const LAS bf16x8*)(lds + kaddr1 + (c) * kcs + 512); } while (0)
; template <bool LOC> ...
;     ...
;     AH_LDK(0, 0);
; #pragma unroll
;     for (int c = 0; c < 8; ++c) {
;         if (c < 7) AH_LDK(c + 1, (c + 1) & 1);
;         __builtin_amdgcn_sched_barrier(0);
;         f32x4 t0 = (f32x4){0.f, 0.f, 0.f, 0.f}, t1 = (f32x4){0.f, 0.f, 0.f, 0.f};
;         t0 = __builtin_amdgcn_mfma_f32_16x16x32_bf16(kf[c & 1][0], q0, t0, 0, 0, 0); t1 = __builtin_amdgcn_mfma_f32_16x16x32_bf16(kf[c & 1][2], q0, t1, 0, 0, 0);
;         t0 = __builtin_amdgcn_mfma_f32_16x16x32_bf16(kf[c & 1][1], q1, t0, 0, 0, 0); t1 = __builtin_amdgcn_mfma_f32_16x16x32_bf16(kf[c & 1][3], q1, t1, 0, 0, 0);
; #pragma unroll
;         for (int e = 0; e < 8; ++e) { const float a = (e < 4) ? t0[e] : t1[e - 4];
;             if (LOC) { const float bv = bp[c * RPB_PITCH + e]; const bool ok = (e >= elo) && (e < elo + 16); s[c][e] = ok ? (a * SC + bv) : -INFINITY; }
;             else s[c][e] = a * SC; }
;         __builtin_amdgcn_sched_barrier(0);
;     }
;     ...
;     float m2 = mx;
; #pragma unroll
;     for (int c = 0; c < 8; ++c)
; #pragma unroll
;         for (int e = 0; e < 8; ++e) m2 = fmaxf(m2, s[c][e]);
;     m2 = fmaxf(m2, __shfl_xor(m2, 16)); m2 = fmaxf(m2, __shfl_xor(m2, 32));
;     const float alpha = __builtin_amdgcn_exp2f(mx - m2);
;     mx = m2; lsum *= alpha;
; #pragma unroll
;     for (int dt = 0; dt < 4; ++dt) o[dt] = o[dt] * alpha;
	v_fmamk_f32 v25, v176, 0x3e38aa3b, v242
	v_fmac_f32_e32 v243, 0x3e38aa3b, v177
	v_cndmask_b32_e64 v175, v222, v25, s[18:19]
	v_cndmask_b32_e64 v173, v222, v243, s[20:21]
	v_mfma_f32_16x16x32_bf16 v[176:179], v[182:185], v[4:7], 0
	v_mfma_f32_16x16x32_bf16 v[4:7], v[186:189], v[4:7], 0
	v_mfma_f32_16x16x32_bf16 v[176:179], v[202:205], v[0:3], v[176:179]
	v_mfma_f32_16x16x32_bf16 v[0:3], v[206:209], v[0:3], v[4:7]
	s_nop 5
	v_add_u32_e32 v4, 0xe7c, v24
	ds_read2_b32 v[4:5], v4 offset1:1
	v_add_u32_e32 v235, 0xe84, v24
	v_add_u32_e32 v236, 0xe8c, v24
	v_add_u32_e32 v237, 0xe94, v24
	ds_read2_b32 v[238:239], v235 offset1:1
	ds_read2_b32 v[240:241], v236 offset1:1
	ds_read2_b32 v[242:243], v237 offset1:1
	s_waitcnt lgkmcnt(0)
	v_fmamk_f32 v4, v176, 0x3e38aa3b, v4
	v_cndmask_b32_e64 v170, v222, v4, s[6:7]
	v_fmac_f32_e32 v5, 0x3e38aa3b, v177
	s_nop 0
	v_cndmask_b32_e64 v167, v222, v5, s[8:9]
	s_nop 0
	s_waitcnt lgkmcnt(0)
	v_fmamk_f32 v4, v178, 0x3e38aa3b, v238
	v_cndmask_b32_e64 v172, v222, v4, s[10:11]
	v_fmac_f32_e32 v239, 0x3e38aa3b, v179
	s_nop 0
	v_cndmask_b32_e64 v171, v222, v239, s[12:13]
	s_nop 0
	s_waitcnt lgkmcnt(0)
	v_fmamk_f32 v0, v0, 0x3e38aa3b, v240
	v_cndmask_b32_e64 v176, v222, v0, s[14:15]
	s_nop 0
	v_fmac_f32_e32 v241, 0x3e38aa3b, v1
	s_nop 0
	v_cndmask_b32_e64 v174, v222, v241, s[16:17]
	s_waitcnt lgkmcnt(0)
	v_fmamk_f32 v0, v2, 0x3e38aa3b, v242
	v_fmac_f32_e32 v243, 0x3e38aa3b, v3
	v_cndmask_b32_e64 v178, v222, v0, s[18:19]
	v_cndmask_b32_e64 v177, v222, v243, s[20:21]
	v_max3_f32 v0, v97, v30, v29
	v_max3_f32 v0, v0, v32, v31
	v_max3_f32 v0, v0, v34, v33
	v_max3_f32 v0, v0, v43, v41
	v_max3_f32 v0, v0, v37, v35
	v_max3_f32 v0, v0, v39, v38
	v_max3_f32 v0, v0, v42, v40
	v_max3_f32 v0, v0, v51, v49
	v_max3_f32 v0, v0, v45, v44
	v_max3_f32 v0, v0, v47, v46
	v_max3_f32 v0, v0, v50, v48
	v_max3_f32 v0, v0, v59, v57
	v_max3_f32 v0, v0, v53, v52
	v_max3_f32 v0, v0, v55, v54
	v_max3_f32 v0, v0, v58, v56
	v_max3_f32 v0, v0, v67, v65
	v_max3_f32 v0, v0, v61, v60
	v_max3_f32 v0, v0, v63, v62
	v_max3_f32 v0, v0, v66, v64
	v_max3_f32 v0, v0, v102, v100
	v_max3_f32 v0, v0, v69, v68
	v_max3_f32 v0, v0, v71, v70
	v_max3_f32 v0, v0, v101, v99
	v_max3_f32 v0, v0, v155, v153
	v_max3_f32 v0, v0, v104, v103
	v_max3_f32 v0, v0, v151, v105
	v_max3_f32 v0, v0, v154, v152
	v_max3_f32 v0, v0, v175, v173
	v_max3_f32 v0, v0, v170, v167
	v_max3_f32 v0, v0, v172, v171
	v_max3_f32 v0, v0, v176, v174
	v_max3_f32 v0, v0, v178, v177
	ds_bpermute_b32 v1, v114, v0
	s_waitcnt lgkmcnt(0)
	v_max_f32_e32 v1, v1, v1
	v_max_f32_e32 v0, v0, v1
	ds_bpermute_b32 v1, v115, v0
	s_waitcnt lgkmcnt(0)
	v_max_f32_e32 v1, v1, v1
	v_max_f32_e32 v179, v0, v1
	v_sub_f32_e32 v0, v97, v179
	v_exp_f32_e32 v204, v0
	s_nop 0
	v_pk_mul_f32 v[24:25], v[8:9], v[204:205] op_sel_hi:[1,0]
	v_pk_mul_f32 v[8:9], v[12:13], v[204:205] op_sel_hi:[1,0]
	v_lshl_add_u32 v12, v36, 3, v112
	v_xor_b32_e32 v13, v12, v107
	v_lshl_add_u32 v13, v13, 4, v113
	v_pk_mul_f32 v[26:27], v[10:11], v[204:205] op_sel_hi:[1,0]
	v_pk_mul_f32 v[10:11], v[14:15], v[204:205] op_sel_hi:[1,0]
	v_pk_mul_f32 v[6:7], v[18:19], v[204:205] op_sel_hi:[1,0]
	v_pk_mul_f32 v[4:5], v[16:17], v[204:205] op_sel_hi:[1,0]
	v_pk_mul_f32 v[0:1], v[20:21], v[204:205] op_sel_hi:[1,0]
	ds_read_b128 v[14:17], v13
	ds_read_b128 v[18:21], v13 offset:20480
	ds_read_b128 v[180:183], v13 offset:40960
	ds_read_b128 v[184:187], v13 offset:61440
	v_add_u32_e32 v13, 8, v12
	v_xor_b32_e32 v13, v13, v107
	v_lshl_add_u32 v13, v13, 4, v113
	ds_read_b128 v[188:191], v13
	ds_read_b128 v[192:195], v13 offset:20480
	ds_read_b128 v[196:199], v13 offset:40960
	ds_read_b128 v[200:203], v13 offset:61440
	v_pk_mul_f32 v[2:3], v[22:23], v[204:205] op_sel_hi:[1,0]
	v_sub_f32_e32 v13, v30, v179
	v_exp_f32_e32 v13, v13
	v_sub_f32_e32 v23, v29, v179
	v_exp_f32_e32 v23, v23
	v_fma_f32 v22, v28, v204, v13
	v_sub_f32_e32 v28, v32, v179
	v_exp_f32_e32 v29, v28
	v_sub_f32_e32 v28, v31, v179
	v_exp_f32_e32 v30, v28
	v_sub_f32_e32 v28, v34, v179
	v_exp_f32_e32 v31, v28
	v_sub_f32_e32 v28, v33, v179
	v_exp_f32_e32 v32, v28
	v_sub_f32_e32 v28, v43, v179
	v_add_f32_e32 v22, v23, v22
	v_exp_f32_e32 v33, v28
	v_sub_f32_e32 v28, v41, v179
	v_add_f32_e32 v22, v29, v22
	v_exp_f32_e32 v34, v28
	v_add_f32_e32 v22, v30, v22
	v_add_f32_e32 v22, v31, v22
	v_add_f32_e32 v22, v32, v22
	v_add_f32_e32 v22, v33, v22
	v_cvt_pk_bf16_f32 v28, v13, v23
	v_cvt_pk_bf16_f32 v29, v29, v30
	v_cvt_pk_bf16_f32 v30, v31, v32
	v_cvt_pk_bf16_f32 v31, v33, v34
	v_add_f32_e32 v36, v34, v22
	s_waitcnt lgkmcnt(7)
	v_mfma_f32_16x16x32_bf16 v[14:17], v[14:17], v[28:31], v[24:27]
	s_waitcnt lgkmcnt(6)
	v_mfma_f32_16x16x32_bf16 v[8:11], v[18:21], v[28:31], v[8:11]
	s_waitcnt lgkmcnt(5)
	v_mfma_f32_16x16x32_bf16 v[4:7], v[180:183], v[28:31], v[4:7]
	s_waitcnt lgkmcnt(4)
	v_mfma_f32_16x16x32_bf16 v[0:3], v[184:187], v[28:31], v[0:3]
	v_add_u32_e32 v13, 16, v12
	v_xor_b32_e32 v13, v13, v107
	v_lshl_add_u32 v13, v13, 4, v113
	ds_read_b128 v[18:21], v13
	ds_read_b128 v[22:25], v13 offset:20480
	ds_read_b128 v[26:29], v13 offset:40960
	ds_read_b128 v[30:33], v13 offset:61440
	v_sub_f32_e32 v13, v37, v179
	v_exp_f32_e32 v13, v13
	v_sub_f32_e32 v35, v35, v179
	v_exp_f32_e32 v35, v35
	v_sub_f32_e32 v37, v38, v179
	v_add_f32_e32 v34, v13, v36
	v_sub_f32_e32 v36, v39, v179
	v_exp_f32_e32 v36, v36
	v_exp_f32_e32 v37, v37
	v_sub_f32_e32 v38, v42, v179
	v_exp_f32_e32 v38, v38
	v_sub_f32_e32 v39, v40, v179
	v_add_f32_e32 v34, v35, v34
	v_exp_f32_e32 v39, v39
	v_sub_f32_e32 v40, v51, v179
	v_add_f32_e32 v34, v36, v34
	v_exp_f32_e32 v40, v40
	v_sub_f32_e32 v41, v49, v179
	v_add_f32_e32 v34, v37, v34
	v_exp_f32_e32 v41, v41
	v_add_f32_e32 v34, v38, v34
	v_add_f32_e32 v34, v39, v34
	v_add_f32_e32 v34, v40, v34
	v_add_f32_e32 v42, v41, v34
	v_cvt_pk_bf16_f32 v34, v13, v35
	v_cvt_pk_bf16_f32 v35, v36, v37
	v_cvt_pk_bf16_f32 v36, v38, v39
	v_cvt_pk_bf16_f32 v37, v40, v41
	s_waitcnt lgkmcnt(7)
; __device__ __forceinline__ unsigned cvt_pk_bf16(float lo, float hi) { const f32x2 v = (f32x2){lo, hi}; return __builtin_bit_cast(unsigned, __builtin_convertvector(v, bf16v2)); }
; #define AH_LDV(c, bufi) do { const int vaddr = vrow + (((vchunk0 + (c) * vcs + g) ^ qi) << 4); _Pragma("unroll") for (int dt = 0; dt < 4; ++dt) vf[bufi][dt] = *(const LAS bf16x8*)(lds + vaddr + dt * vpitch_dt); } while (0)
; template <bool LOC> ...
;     ...
;     AH_LDV(0, 0);
; #pragma unroll
;     for (int c = 0; c < 8; ++c) {
;         if (c < 7) AH_LDV(c + 1, (c + 1) & 1);
;         __builtin_amdgcn_sched_barrier(0);
;         float pe[8];
; #pragma unroll
;         for (int e = 0; e < 8; ++e) { pe[e] = __builtin_amdgcn_exp2f(s[c][e] - mx); lsum += pe[e]; }
;         u32x4 pw; pw.x = cvt_pk_bf16(pe[0], pe[1]); pw.y = cvt_pk_bf16(pe[2], pe[3]); pw.z = cvt_pk_bf16(pe[4], pe[5]); pw.w = cvt_pk_bf16(pe[6], pe[7]);
;         const bf16x8 pb = __builtin_bit_cast(bf16x8, pw);
; #pragma unroll
;         for (int dt = 0; dt < 4; ++dt) o[dt] = __builtin_amdgcn_mfma_f32_16x16x32_bf16(vf[c & 1][dt], pb, o[dt], 0, 0, 0);
;         __builtin_amdgcn_sched_barrier(0);
;     }
	s_nop 0
	v_mfma_f32_16x16x32_bf16 v[14:17], v[188:191], v[34:37], v[14:17]
	s_waitcnt lgkmcnt(6)
	v_mfma_f32_16x16x32_bf16 v[8:11], v[192:195], v[34:37], v[8:11]
	s_waitcnt lgkmcnt(5)
	v_mfma_f32_16x16x32_bf16 v[4:7], v[196:199], v[34:37], v[4:7]
	s_waitcnt lgkmcnt(4)
	v_mfma_f32_16x16x32_bf16 v[0:3], v[200:203], v[34:37], v[0:3]
	v_add_u32_e32 v13, 24, v12
	v_xor_b32_e32 v13, v13, v107
	v_lshl_add_u32 v13, v13, 4, v113
	ds_read_b128 v[34:37], v13
	ds_read_b128 v[38:41], v13 offset:20480
	ds_read_b128 v[180:183], v13 offset:40960
	ds_read_b128 v[184:187], v13 offset:61440
	v_sub_f32_e32 v13, v45, v179
	v_exp_f32_e32 v13, v13
	v_sub_f32_e32 v43, v44, v179
	v_exp_f32_e32 v43, v43
	v_sub_f32_e32 v44, v47, v179
	v_exp_f32_e32 v44, v44
	v_sub_f32_e32 v45, v46, v179
	v_exp_f32_e32 v45, v45
	v_sub_f32_e32 v46, v50, v179
	v_add_f32_e32 v42, v13, v42
	v_exp_f32_e32 v46, v46
	v_sub_f32_e32 v47, v48, v179
	v_add_f32_e32 v42, v43, v42
	v_exp_f32_e32 v47, v47
	v_sub_f32_e32 v48, v59, v179
	v_add_f32_e32 v42, v44, v42
	v_exp_f32_e32 v48, v48
	v_sub_f32_e32 v49, v57, v179
	v_add_f32_e32 v42, v45, v42
	v_exp_f32_e32 v49, v49
	v_add_f32_e32 v42, v46, v42
	v_add_f32_e32 v42, v47, v42
	v_add_f32_e32 v42, v48, v42
	v_add_f32_e32 v50, v49, v42
	v_cvt_pk_bf16_f32 v42, v13, v43
	v_cvt_pk_bf16_f32 v43, v44, v45
	v_cvt_pk_bf16_f32 v44, v46, v47
	v_cvt_pk_bf16_f32 v45, v48, v49
	s_waitcnt lgkmcnt(7)
	s_nop 0
	v_mfma_f32_16x16x32_bf16 v[14:17], v[18:21], v[42:45], v[14:17]
	s_waitcnt lgkmcnt(6)
	v_mfma_f32_16x16x32_bf16 v[8:11], v[22:25], v[42:45], v[8:11]
	s_waitcnt lgkmcnt(5)
	v_mfma_f32_16x16x32_bf16 v[4:7], v[26:29], v[42:45], v[4:7]
	s_waitcnt lgkmcnt(4)
	v_mfma_f32_16x16x32_bf16 v[0:3], v[30:33], v[42:45], v[0:3]
	v_add_u32_e32 v13, 32, v12
	v_xor_b32_e32 v13, v13, v107
	v_lshl_add_u32 v13, v13, 4, v113
	ds_read_b128 v[18:21], v13
	ds_read_b128 v[22:25], v13 offset:20480
	ds_read_b128 v[26:29], v13 offset:40960
	ds_read_b128 v[30:33], v13 offset:61440
	v_sub_f32_e32 v13, v53, v179
	v_exp_f32_e32 v13, v13
	v_sub_f32_e32 v43, v52, v179
	v_exp_f32_e32 v43, v43
	v_sub_f32_e32 v44, v55, v179
	v_exp_f32_e32 v44, v44
	v_sub_f32_e32 v45, v54, v179
	v_exp_f32_e32 v45, v45
	v_sub_f32_e32 v46, v58, v179
	v_add_f32_e32 v42, v13, v50
	v_exp_f32_e32 v46, v46
	v_sub_f32_e32 v47, v56, v179
	v_add_f32_e32 v42, v43, v42
	v_exp_f32_e32 v47, v47
	v_sub_f32_e32 v48, v67, v179
	v_add_f32_e32 v42, v44, v42
	v_exp_f32_e32 v48, v48
	v_sub_f32_e32 v49, v65, v179
	v_add_f32_e32 v42, v45, v42
	v_exp_f32_e32 v49, v49
	v_add_f32_e32 v42, v46, v42
	v_add_f32_e32 v42, v47, v42
	v_add_f32_e32 v42, v48, v42
	v_add_f32_e32 v50, v49, v42
	v_cvt_pk_bf16_f32 v42, v13, v43
	v_cvt_pk_bf16_f32 v43, v44, v45
	v_cvt_pk_bf16_f32 v44, v46, v47
	v_cvt_pk_bf16_f32 v45, v48, v49
	s_waitcnt lgkmcnt(7)
	s_nop 0
	v_mfma_f32_16x16x32_bf16 v[14:17], v[34:37], v[42:45], v[14:17]
	s_waitcnt lgkmcnt(6)
	v_mfma_f32_16x16x32_bf16 v[8:11], v[38:41], v[42:45], v[8:11]
	s_waitcnt lgkmcnt(5)
	v_mfma_f32_16x16x32_bf16 v[4:7], v[180:183], v[42:45], v[4:7]
	s_waitcnt lgkmcnt(4)
	v_mfma_f32_16x16x32_bf16 v[0:3], v[184:187], v[42:45], v[0:3]
	v_add_u32_e32 v13, 40, v12
	v_xor_b32_e32 v13, v13, v107
	v_lshl_add_u32 v13, v13, 4, v113
	ds_read_b128 v[34:37], v13
	ds_read_b128 v[38:41], v13 offset:20480
	ds_read_b128 v[42:45], v13 offset:40960
	ds_read_b128 v[46:49], v13 offset:61440
	v_sub_f32_e32 v13, v61, v179
	v_exp_f32_e32 v13, v13
	v_sub_f32_e32 v51, v60, v179
	v_exp_f32_e32 v51, v51
	v_sub_f32_e32 v52, v63, v179
	v_exp_f32_e32 v52, v52
	v_sub_f32_e32 v53, v62, v179
	v_exp_f32_e32 v53, v53
	v_sub_f32_e32 v54, v66, v179
	v_add_f32_e32 v50, v13, v50
	v_exp_f32_e32 v54, v54
	v_sub_f32_e32 v55, v64, v179
	v_add_f32_e32 v50, v51, v50
	v_exp_f32_e32 v55, v55
	v_sub_f32_e32 v56, v102, v179
	v_add_f32_e32 v50, v52, v50
	v_exp_f32_e32 v56, v56
	v_sub_f32_e32 v57, v100, v179
	v_add_f32_e32 v50, v53, v50
	v_exp_f32_e32 v57, v57
	v_add_f32_e32 v50, v54, v50
	v_add_f32_e32 v50, v55, v50
	v_add_f32_e32 v50, v56, v50
	v_add_f32_e32 v58, v57, v50
	v_cvt_pk_bf16_f32 v50, v13, v51
	v_cvt_pk_bf16_f32 v51, v52, v53
	v_cvt_pk_bf16_f32 v52, v54, v55
	v_cvt_pk_bf16_f32 v53, v56, v57
	s_waitcnt lgkmcnt(7)
	s_nop 0
	v_mfma_f32_16x16x32_bf16 v[14:17], v[18:21], v[50:53], v[14:17]
	s_waitcnt lgkmcnt(6)
	v_mfma_f32_16x16x32_bf16 v[8:11], v[22:25], v[50:53], v[8:11]
	s_waitcnt lgkmcnt(5)
	v_mfma_f32_16x16x32_bf16 v[4:7], v[26:29], v[50:53], v[4:7]
	s_waitcnt lgkmcnt(4)
	v_mfma_f32_16x16x32_bf16 v[0:3], v[30:33], v[50:53], v[0:3]
	v_add_u32_e32 v13, 48, v12
	v_xor_b32_e32 v13, v13, v107
	v_lshl_add_u32 v13, v13, 4, v113
	ds_read_b128 v[18:21], v13
	ds_read_b128 v[22:25], v13 offset:20480
	ds_read_b128 v[26:29], v13 offset:40960
	ds_read_b128 v[30:33], v13 offset:61440
	v_sub_f32_e32 v13, v69, v179
	v_exp_f32_e32 v13, v13
	v_sub_f32_e32 v51, v68, v179
	v_exp_f32_e32 v51, v51
	v_sub_f32_e32 v52, v71, v179
	v_exp_f32_e32 v52, v52
	v_sub_f32_e32 v53, v70, v179
	v_exp_f32_e32 v53, v53
	v_sub_f32_e32 v54, v101, v179
	v_add_f32_e32 v50, v13, v58
	v_exp_f32_e32 v54, v54
	v_sub_f32_e32 v55, v99, v179
	v_add_f32_e32 v50, v51, v50
	v_exp_f32_e32 v55, v55
	v_sub_f32_e32 v56, v155, v179
	v_add_f32_e32 v50, v52, v50
	v_exp_f32_e32 v56, v56
	v_sub_f32_e32 v57, v153, v179
	v_add_f32_e32 v50, v53, v50
	v_exp_f32_e32 v57, v57
	v_add_f32_e32 v50, v54, v50
	v_add_f32_e32 v50, v55, v50
	v_add_f32_e32 v50, v56, v50
	v_add_f32_e32 v58, v57, v50
	v_cvt_pk_bf16_f32 v50, v13, v51
	v_cvt_pk_bf16_f32 v51, v52, v53
	v_cvt_pk_bf16_f32 v52, v54, v55
	v_cvt_pk_bf16_f32 v53, v56, v57
	s_waitcnt lgkmcnt(7)
; __device__ __forceinline__ unsigned cvt_pk_bf16(float lo, float hi) { const f32x2 v = (f32x2){lo, hi}; return __builtin_bit_cast(unsigned, __builtin_convertvector(v, bf16v2)); }
; template <bool LOC> ...
;     ...
;         for (int e = 0; e < 8; ++e) { pe[e] = __builtin_amdgcn_exp2f(s[c][e] - mx); lsum += pe[e]; }
;         u32x4 pw; pw.x = cvt_pk_bf16(pe[0], pe[1]); pw.y = cvt_pk_bf16(pe[2], pe[3]); pw.z = cvt_pk_bf16(pe[4], pe[5]); pw.w = cvt_pk_bf16(pe[6], pe[7]);
;         const bf16x8 pb = __builtin_bit_cast(bf16x8, pw);
; #pragma unroll
;         for (int dt = 0; dt < 4; ++dt) o[dt] = __builtin_amdgcn_mfma_f32_16x16x32_bf16(vf[c & 1][dt], pb, o[dt], 0, 0, 0);
;         __builtin_amdgcn_sched_barrier(0);
;     }
;     ...
; }
; __device__ __forceinline__ void attn_store(bf16_t* MIX, int qtok, int h, int g, float lsum, const f32x4 (&o)[4]) {
;     lsum += __shfl_xor(lsum, 16); lsum += __shfl_xor(lsum, 32);
;     const float inv = 1.f / lsum;
;     bf16_t* op = MIX + (size_t)qtok * DM + 512 + h * 64 + 4 * g;
; #pragma unroll
;     for (int dt = 0; dt < 4; ++dt) { u32x2 w; w.x = cvt_pk_bf16(o[dt][0] * inv, o[dt][1] * inv); w.y = cvt_pk_bf16(o[dt][2] * inv, o[dt][3] * inv); *(u32x2*)(op + 16 * dt) = w; }
; }
; __device__ __forceinline__ void phase_mixer(const Params& p, LAS unsigned char* lds, int l, bool with_ctx, int G, int tid, int wave, int lane, int rep_attn, int rep_pool) {
;     ...
;             attn_store(MIX, b * SEQ + r * 64 + 16 * n + qi, h, g, lA, oA);
;         }
;         __syncthreads();
	s_nop 0
	v_mfma_f32_16x16x32_bf16 v[14:17], v[34:37], v[50:53], v[14:17]
	s_waitcnt lgkmcnt(6)
	v_mfma_f32_16x16x32_bf16 v[8:11], v[38:41], v[50:53], v[8:11]
	s_waitcnt lgkmcnt(5)
	v_mfma_f32_16x16x32_bf16 v[4:7], v[42:45], v[50:53], v[4:7]
	s_waitcnt lgkmcnt(4)
	v_mfma_f32_16x16x32_bf16 v[0:3], v[46:49], v[50:53], v[0:3]
	v_add_u32_e32 v12, 56, v12
	v_xor_b32_e32 v12, v12, v107
	v_lshl_add_u32 v12, v12, 4, v113
	ds_read_b128 v[34:37], v12
	ds_read_b128 v[38:41], v12 offset:20480
	ds_read_b128 v[42:45], v12 offset:40960
	ds_read_b128 v[46:49], v12 offset:61440
	v_sub_f32_e32 v12, v104, v179
	v_exp_f32_e32 v12, v12
	v_sub_f32_e32 v50, v103, v179
	v_exp_f32_e32 v50, v50
	v_sub_f32_e32 v51, v151, v179
	v_exp_f32_e32 v51, v51
	v_sub_f32_e32 v52, v105, v179
	v_exp_f32_e32 v52, v52
	v_sub_f32_e32 v53, v154, v179
	v_add_f32_e32 v13, v12, v58
	v_exp_f32_e32 v53, v53
	v_sub_f32_e32 v54, v152, v179
	v_add_f32_e32 v13, v50, v13
	v_exp_f32_e32 v54, v54
	v_sub_f32_e32 v55, v175, v179
	v_sub_f32_e32 v56, v173, v179
	v_add_f32_e32 v13, v51, v13
	v_exp_f32_e32 v55, v55
	v_exp_f32_e32 v56, v56
	v_add_f32_e32 v13, v52, v13
	v_add_f32_e32 v13, v53, v13
	v_add_f32_e32 v13, v54, v13
	v_add_f32_e32 v13, v55, v13
	v_cvt_pk_bf16_f32 v50, v12, v50
	v_cvt_pk_bf16_f32 v51, v51, v52
	v_cvt_pk_bf16_f32 v52, v53, v54
	v_cvt_pk_bf16_f32 v53, v55, v56
	v_add_f32_e32 v57, v56, v13
	s_waitcnt lgkmcnt(7)
	v_mfma_f32_16x16x32_bf16 v[12:15], v[18:21], v[50:53], v[14:17]
	s_waitcnt lgkmcnt(6)
	v_mfma_f32_16x16x32_bf16 v[8:11], v[22:25], v[50:53], v[8:11]
	s_waitcnt lgkmcnt(5)
	v_mfma_f32_16x16x32_bf16 v[4:7], v[26:29], v[50:53], v[4:7]
	s_waitcnt lgkmcnt(4)
	v_mfma_f32_16x16x32_bf16 v[0:3], v[30:33], v[50:53], v[0:3]
	v_sub_f32_e32 v16, v170, v179
	v_exp_f32_e32 v16, v16
	v_sub_f32_e32 v18, v167, v179
	v_exp_f32_e32 v18, v18
	v_sub_f32_e32 v19, v172, v179
	v_exp_f32_e32 v19, v19
	v_sub_f32_e32 v20, v171, v179
	v_exp_f32_e32 v20, v20
	v_sub_f32_e32 v21, v176, v179
	v_add_f32_e32 v17, v16, v57
	v_exp_f32_e32 v21, v21
	v_sub_f32_e32 v22, v174, v179
	v_add_f32_e32 v17, v18, v17
	v_exp_f32_e32 v22, v22
	v_sub_f32_e32 v23, v178, v179
	v_add_f32_e32 v17, v19, v17
	v_exp_f32_e32 v23, v23
	v_sub_f32_e32 v24, v177, v179
	v_add_f32_e32 v17, v20, v17
	v_exp_f32_e32 v24, v24
	v_add_f32_e32 v17, v21, v17
	v_add_f32_e32 v17, v22, v17
	v_add_f32_e32 v17, v23, v17
	v_add_f32_e32 v25, v24, v17
	v_cvt_pk_bf16_f32 v16, v16, v18
	v_cvt_pk_bf16_f32 v17, v19, v20
	v_cvt_pk_bf16_f32 v18, v21, v22
	v_cvt_pk_bf16_f32 v19, v23, v24
	s_waitcnt lgkmcnt(3)
	s_nop 0
	v_mfma_f32_16x16x32_bf16 v[12:15], v[34:37], v[16:19], v[12:15]
	s_waitcnt lgkmcnt(2)
	v_mfma_f32_16x16x32_bf16 v[8:11], v[38:41], v[16:19], v[8:11]
	s_waitcnt lgkmcnt(1)
	v_mfma_f32_16x16x32_bf16 v[4:7], v[42:45], v[16:19], v[4:7]
	s_waitcnt lgkmcnt(0)
	v_mfma_f32_16x16x32_bf16 v[0:3], v[46:49], v[16:19], v[0:3]
	ds_bpermute_b32 v17, v114, v25
	v_or_b32_e32 v16, s62, v108
	v_mov_b32_e32 v99, v157
	s_add_i32 s61, s61, s3
	s_cmpk_gt_i32 s61, 0x7ff
	s_waitcnt lgkmcnt(0)
	v_add_f32_e32 v18, v25, v17
	ds_bpermute_b32 v19, v115, v18
	v_ashrrev_i32_e32 v17, 31, v16
	v_lshlrev_b64 v[16:17], 11, v[16:17]
	v_lshl_add_u64 v[16:17], s[26:27], 0, v[16:17]
	v_lshl_add_u64 v[16:17], v[16:17], 0, s[30:31]
	s_waitcnt lgkmcnt(0)
	v_add_f32_e32 v18, v18, v19
	v_div_scale_f32 v19, s[62:63], v18, v18, 1.0
	v_rcp_f32_e32 v20, v19
	v_div_scale_f32 v21, vcc, 1.0, v18, 1.0
	v_lshl_add_u64 v[16:17], v[16:17], 0, v[98:99]
	v_fma_f32 v22, -v19, v20, 1.0
	v_fmac_f32_e32 v20, v22, v20
	v_mul_f32_e32 v22, v21, v20
	v_fma_f32 v23, -v19, v22, v21
	v_fmac_f32_e32 v22, v23, v20
	v_fma_f32 v19, -v19, v22, v21
	v_div_fmas_f32 v19, v19, v20, v22
	v_div_fixup_f32 v18, v19, v18, 1.0
	v_pk_mul_f32 v[12:13], v[12:13], v[18:19] op_sel_hi:[1,0]
	v_pk_mul_f32 v[14:15], v[14:15], v[18:19] op_sel_hi:[1,0]
	v_pk_mul_f32 v[8:9], v[8:9], v[18:19] op_sel_hi:[1,0]
	v_pk_mul_f32 v[10:11], v[10:11], v[18:19] op_sel_hi:[1,0]
	v_pk_mul_f32 v[4:5], v[4:5], v[18:19] op_sel_hi:[1,0]
	v_pk_mul_f32 v[6:7], v[6:7], v[18:19] op_sel_hi:[1,0]
	v_pk_mul_f32 v[0:1], v[0:1], v[18:19] op_sel_hi:[1,0]
	v_pk_mul_f32 v[2:3], v[2:3], v[18:19] op_sel_hi:[1,0]
	v_cvt_pk_bf16_f32 v12, v12, v13
	v_cvt_pk_bf16_f32 v13, v14, v15
	v_cvt_pk_bf16_f32 v8, v8, v9
	v_cvt_pk_bf16_f32 v9, v10, v11
	v_cvt_pk_bf16_f32 v4, v4, v5
	v_cvt_pk_bf16_f32 v5, v6, v7
	v_cvt_pk_bf16_f32 v0, v0, v1
	v_cvt_pk_bf16_f32 v1, v2, v3
	global_store_dwordx2 v[16:17], v[12:13], off offset:1024
	global_store_dwordx2 v[16:17], v[8:9], off offset:1056
	global_store_dwordx2 v[16:17], v[4:5], off offset:1088
	global_store_dwordx2 v[16:17], v[0:1], off offset:1120
	s_barrier
	s_cbranch_scc1 .LBB0_306
